# v34 + out-proj/FFN-out GEMM last k-iteration: the 14 freed LDS-DMA slots issue 4-byte touch loads of the residual tile rows so the epilogue's residual loads hit L2
# speedup vs baseline: 1.0080x; 1.0061x over previous
.LBB0_1179:
	s_add_i32 s92, s42, 2
	s_add_u32 s72, s36, 0x80
	s_addc_u32 s43, s37, 0
	s_add_i32 s93, 0, 0x10000
	v_add_u32_e32 v1, s93, v223
	ds_read_b128 v[50:53], v1
	ds_read_b128 v[54:57], v1 offset:1024
	ds_read_b128 v[58:61], v1 offset:2048
	ds_read_b128 v[62:65], v1 offset:3072
	s_cmp_eq_u32 s88, s42
	s_cselect_b32 s42, s66, s72
	s_cselect_b32 s43, s67, s43
	s_cselect_b32 s73, s71, s91
	s_cselect_b32 s72, s70, s27
	v_lshl_add_u64 v[178:179], s[36:37], 0, v[206:207]
	s_add_i32 m0, s79, 0xc000
	ds_read_b128 v[66:69], v230
	ds_read_b128 v[70:73], v230 offset:1024
	ds_read_b128 v[74:77], v230 offset:2048
	ds_read_b128 v[78:81], v230 offset:3072
	ds_read_b128 v[146:149], v230 offset:4096
	ds_read_b128 v[154:157], v230 offset:5120
	ds_read_b128 v[170:173], v230 offset:6144
	ds_read_b128 v[174:177], v230 offset:7168
	global_load_lds_dwordx4 v[178:179], off
	v_lshl_add_u64 v[178:179], s[36:37], 0, v[204:205]
	s_add_i32 m0, s79, 0xe000
	s_nop 0
	global_load_lds_dwordx4 v[178:179], off
	s_waitcnt lgkmcnt(8)
	s_barrier
	s_waitcnt lgkmcnt(0)
	s_waitcnt lgkmcnt(0)
	v_mfma_f32_16x16x32_bf16 v[166:169], v[50:53], v[66:69], v[166:169]
	v_mfma_f32_16x16x32_bf16 v[162:165], v[58:61], v[66:69], v[162:165]
	v_mfma_f32_16x16x32_bf16 v[142:145], v[50:53], v[74:77], v[142:145]
	v_mfma_f32_16x16x32_bf16 v[138:141], v[58:61], v[74:77], v[138:141]
	v_mfma_f32_16x16x32_bf16 v[126:129], v[50:53], v[146:149], v[126:129]
	v_mfma_f32_16x16x32_bf16 v[122:125], v[58:61], v[146:149], v[122:125]
	v_mfma_f32_16x16x32_bf16 v[110:113], v[50:53], v[170:173], v[110:113]
	v_mfma_f32_16x16x32_bf16 v[106:109], v[58:61], v[170:173], v[106:109]
	v_mfma_f32_16x16x32_bf16 v[166:169], v[54:57], v[70:73], v[166:169]
	v_mfma_f32_16x16x32_bf16 v[162:165], v[62:65], v[70:73], v[162:165]
	v_mfma_f32_16x16x32_bf16 v[142:145], v[54:57], v[78:81], v[142:145]
	v_mfma_f32_16x16x32_bf16 v[138:141], v[62:65], v[78:81], v[138:141]
	v_mfma_f32_16x16x32_bf16 v[126:129], v[54:57], v[154:157], v[126:129]
	v_mfma_f32_16x16x32_bf16 v[122:125], v[62:65], v[154:157], v[122:125]
	v_mfma_f32_16x16x32_bf16 v[110:113], v[54:57], v[174:177], v[110:113]
	v_mfma_f32_16x16x32_bf16 v[106:109], v[62:65], v[174:177], v[106:109]
	s_barrier
	s_add_i32 s94, 0, 0x14000
	s_add_i32 s93, s93, s78
	v_add_u32_e32 v1, s94, v223
	v_lshl_add_u64 v[214:215], s[72:73], 0, v[202:203]
	s_mov_b32 m0, s93
	ds_read_b128 v[178:181], v1
	ds_read_b128 v[182:185], v1 offset:1024
	ds_read_b128 v[186:189], v1 offset:2048
	ds_read_b128 v[190:193], v1 offset:3072
	global_load_lds_dwordx4 v[214:215], off
	v_lshl_add_u64 v[236:237], s[72:73], 0, v[200:201]
	s_add_i32 m0, s93, 0x2000
	s_nop 0
	global_load_lds_dwordx4 v[236:237], off
	s_barrier
	s_waitcnt lgkmcnt(0)
	s_waitcnt lgkmcnt(0)
	v_mfma_f32_16x16x32_bf16 v[158:161], v[178:181], v[66:69], v[158:161]
	v_mfma_f32_16x16x32_bf16 v[66:69], v[186:189], v[66:69], v[150:153]
	v_mfma_f32_16x16x32_bf16 v[158:161], v[182:185], v[70:73], v[158:161]
	v_mfma_f32_16x16x32_bf16 v[66:69], v[190:193], v[70:73], v[66:69]
	v_mfma_f32_16x16x32_bf16 v[70:73], v[178:181], v[74:77], v[134:137]
	v_mfma_f32_16x16x32_bf16 v[74:77], v[186:189], v[74:77], v[130:133]
	v_mfma_f32_16x16x32_bf16 v[114:117], v[186:189], v[146:149], v[114:117]
	v_mfma_f32_16x16x32_bf16 v[102:105], v[178:181], v[170:173], v[102:105]
	v_mfma_f32_16x16x32_bf16 v[98:101], v[186:189], v[170:173], v[98:101]
	v_mfma_f32_16x16x32_bf16 v[70:73], v[182:185], v[78:81], v[70:73]
	v_mfma_f32_16x16x32_bf16 v[74:77], v[190:193], v[78:81], v[74:77]
	v_mfma_f32_16x16x32_bf16 v[78:81], v[178:181], v[146:149], v[118:121]
	v_mfma_f32_16x16x32_bf16 v[114:117], v[190:193], v[154:157], v[114:117]
	v_mfma_f32_16x16x32_bf16 v[102:105], v[182:185], v[174:177], v[102:105]
	v_mfma_f32_16x16x32_bf16 v[98:101], v[190:193], v[174:177], v[98:101]
	v_mfma_f32_16x16x32_bf16 v[78:81], v[182:185], v[154:157], v[78:81]
	s_mov_b32 m0, s79
	v_lshl_add_u64 v[238:239], s[42:43], 0, v[202:203]
	s_barrier
	ds_read_b128 v[118:121], v230 offset:16384
	ds_read_b128 v[130:133], v230 offset:17408
	ds_read_b128 v[134:137], v230 offset:18432
	ds_read_b128 v[146:149], v230 offset:19456
	ds_read_b128 v[150:153], v230 offset:20480
	ds_read_b128 v[154:157], v230 offset:21504
	ds_read_b128 v[170:173], v230 offset:22528
	ds_read_b128 v[174:177], v230 offset:23552
	global_load_lds_dwordx4 v[238:239], off
	v_lshl_add_u64 v[240:241], s[42:43], 0, v[200:201]
	s_mov_b32 m0, s80
	s_nop 0
	global_load_lds_dwordx4 v[240:241], off
	s_barrier
	s_waitcnt lgkmcnt(0)
	s_waitcnt lgkmcnt(0)
	v_mfma_f32_16x16x32_bf16 v[94:97], v[50:53], v[118:121], v[94:97]
	v_mfma_f32_16x16x32_bf16 v[90:93], v[58:61], v[118:121], v[90:93]
	v_mfma_f32_16x16x32_bf16 v[46:49], v[50:53], v[134:137], v[46:49]
	v_mfma_f32_16x16x32_bf16 v[42:45], v[58:61], v[134:137], v[42:45]
	v_mfma_f32_16x16x32_bf16 v[30:33], v[50:53], v[150:153], v[30:33]
	v_mfma_f32_16x16x32_bf16 v[26:29], v[58:61], v[150:153], v[26:29]
	v_mfma_f32_16x16x32_bf16 v[14:17], v[50:53], v[170:173], v[14:17]
	v_mfma_f32_16x16x32_bf16 v[10:13], v[58:61], v[170:173], v[10:13]
	v_mfma_f32_16x16x32_bf16 v[94:97], v[54:57], v[130:133], v[94:97]
	v_mfma_f32_16x16x32_bf16 v[90:93], v[62:65], v[130:133], v[90:93]
	v_mfma_f32_16x16x32_bf16 v[46:49], v[54:57], v[146:149], v[46:49]
	v_mfma_f32_16x16x32_bf16 v[42:45], v[62:65], v[146:149], v[42:45]
	v_mfma_f32_16x16x32_bf16 v[30:33], v[54:57], v[154:157], v[30:33]
	v_mfma_f32_16x16x32_bf16 v[26:29], v[62:65], v[154:157], v[26:29]
	v_mfma_f32_16x16x32_bf16 v[14:17], v[54:57], v[174:177], v[14:17]
	v_mfma_f32_16x16x32_bf16 v[10:13], v[62:65], v[174:177], v[10:13]
	s_barrier
	s_add_u32 s72, s72, s4
	s_addc_u32 s73, s73, 0
	s_add_i32 s93, s94, s78
	v_lshl_add_u64 v[242:243], s[72:73], 0, v[202:203]
	s_mov_b32 m0, s93
	v_lshl_add_u64 v[244:245], s[72:73], 0, v[200:201]
	global_load_lds_dwordx4 v[242:243], off
	s_add_i32 m0, s93, 0x2000
	s_nop 0
	global_load_lds_dwordx4 v[244:245], off
	s_waitcnt vmcnt(6)
	s_barrier
	v_mfma_f32_16x16x32_bf16 v[38:41], v[178:181], v[134:137], v[38:41]
	v_mfma_f32_16x16x32_bf16 v[34:37], v[186:189], v[134:137], v[34:37]
	v_mfma_f32_16x16x32_bf16 v[22:25], v[178:181], v[150:153], v[22:25]
	v_mfma_f32_16x16x32_bf16 v[18:21], v[186:189], v[150:153], v[18:21]
	v_mfma_f32_16x16x32_bf16 v[6:9], v[178:181], v[170:173], v[6:9]
	v_mfma_f32_16x16x32_bf16 v[2:5], v[186:189], v[170:173], v[2:5]
	v_mfma_f32_16x16x32_bf16 v[50:53], v[178:181], v[118:121], v[86:89]
	v_mfma_f32_16x16x32_bf16 v[54:57], v[186:189], v[118:121], v[82:85]
	v_mfma_f32_16x16x32_bf16 v[38:41], v[182:185], v[146:149], v[38:41]
	v_mfma_f32_16x16x32_bf16 v[34:37], v[190:193], v[146:149], v[34:37]
	v_mfma_f32_16x16x32_bf16 v[22:25], v[182:185], v[154:157], v[22:25]
	v_mfma_f32_16x16x32_bf16 v[18:21], v[190:193], v[154:157], v[18:21]
	v_mfma_f32_16x16x32_bf16 v[6:9], v[182:185], v[174:177], v[6:9]
	v_mfma_f32_16x16x32_bf16 v[2:5], v[190:193], v[174:177], v[2:5]
	v_mfma_f32_16x16x32_bf16 v[50:53], v[182:185], v[130:133], v[50:53]
	v_mfma_f32_16x16x32_bf16 v[54:57], v[190:193], v[130:133], v[54:57]
	s_add_i32 s72, 0, 0x18000
	v_add_u32_e32 v1, s72, v223
	s_barrier
	ds_read_b128 v[58:61], v1
	ds_read_b128 v[62:65], v1 offset:1024
	ds_read_b128 v[82:85], v1 offset:2048
	ds_read_b128 v[86:89], v1 offset:3072
	s_add_u32 s42, s42, s4
	s_addc_u32 s43, s43, 0
	s_mov_b32 m0, s81
	v_lshl_add_u64 v[134:135], s[42:43], 0, v[202:203]
	ds_read_b128 v[118:121], v230 offset:32768
	ds_read_b128 v[130:133], v230 offset:33792
	ds_read_b128 v[146:149], v230 offset:34816
	ds_read_b128 v[154:157], v230 offset:35840
	ds_read_b128 v[170:173], v230 offset:36864
	ds_read_b128 v[174:177], v230 offset:37888
	ds_read_b128 v[178:181], v230 offset:38912
	ds_read_b128 v[182:185], v230 offset:39936
	global_load_lds_dwordx4 v[134:135], off
	v_lshl_add_u64 v[134:135], s[42:43], 0, v[200:201]
	s_mov_b32 m0, s82
	s_nop 0
	global_load_lds_dwordx4 v[134:135], off
	s_waitcnt lgkmcnt(8)
	s_barrier
	s_waitcnt lgkmcnt(0)
	s_waitcnt lgkmcnt(0)
	v_mfma_f32_16x16x32_bf16 v[134:137], v[58:61], v[118:121], v[166:169]
	v_mfma_f32_16x16x32_bf16 v[166:169], v[62:65], v[130:133], v[134:137]
	v_mfma_f32_16x16x32_bf16 v[134:137], v[82:85], v[118:121], v[162:165]
	v_mfma_f32_16x16x32_bf16 v[162:165], v[86:89], v[130:133], v[134:137]
	v_mfma_f32_16x16x32_bf16 v[134:137], v[58:61], v[146:149], v[142:145]
	v_mfma_f32_16x16x32_bf16 v[142:145], v[62:65], v[154:157], v[134:137]
	v_mfma_f32_16x16x32_bf16 v[134:137], v[82:85], v[146:149], v[138:141]
	v_mfma_f32_16x16x32_bf16 v[126:129], v[58:61], v[170:173], v[126:129]
	v_mfma_f32_16x16x32_bf16 v[122:125], v[82:85], v[170:173], v[122:125]
	v_mfma_f32_16x16x32_bf16 v[110:113], v[58:61], v[178:181], v[110:113]
	v_mfma_f32_16x16x32_bf16 v[106:109], v[82:85], v[178:181], v[106:109]
	v_mfma_f32_16x16x32_bf16 v[138:141], v[86:89], v[154:157], v[134:137]
	v_mfma_f32_16x16x32_bf16 v[126:129], v[62:65], v[174:177], v[126:129]
	v_mfma_f32_16x16x32_bf16 v[122:125], v[86:89], v[174:177], v[122:125]
	v_mfma_f32_16x16x32_bf16 v[110:113], v[62:65], v[182:185], v[110:113]
	v_mfma_f32_16x16x32_bf16 v[106:109], v[86:89], v[182:185], v[106:109]
	s_barrier
	s_add_i32 s42, 0, 0x1c000
	s_add_i32 s43, s72, s78
	v_add_u32_e32 v1, s42, v223
	v_lshl_add_u64 v[134:135], v[214:215], 0, s[22:23]
	s_mov_b32 m0, s43
	ds_read_b128 v[186:189], v1
	ds_read_b128 v[190:193], v1 offset:1024
	ds_read_b128 v[208:211], v1 offset:2048
	ds_read_b128 v[232:235], v1 offset:3072
	global_load_lds_dwordx4 v[134:135], off
	v_lshl_add_u64 v[134:135], v[236:237], 0, s[22:23]
	s_add_i32 m0, s43, 0x2000
	s_nop 0
	global_load_lds_dwordx4 v[134:135], off
	s_barrier
	s_waitcnt lgkmcnt(0)
	s_waitcnt lgkmcnt(0)
	v_mfma_f32_16x16x32_bf16 v[66:69], v[208:211], v[118:121], v[66:69]
	v_mfma_f32_16x16x32_bf16 v[134:137], v[186:189], v[118:121], v[158:161]
	v_mfma_f32_16x16x32_bf16 v[150:153], v[232:235], v[130:133], v[66:69]
	v_mfma_f32_16x16x32_bf16 v[66:69], v[186:189], v[146:149], v[70:73]
	v_mfma_f32_16x16x32_bf16 v[158:161], v[190:193], v[130:133], v[134:137]
	v_mfma_f32_16x16x32_bf16 v[134:137], v[190:193], v[154:157], v[66:69]
	v_mfma_f32_16x16x32_bf16 v[66:69], v[208:211], v[146:149], v[74:77]
	v_mfma_f32_16x16x32_bf16 v[130:133], v[232:235], v[154:157], v[66:69]
	v_mfma_f32_16x16x32_bf16 v[66:69], v[186:189], v[170:173], v[78:81]
	v_mfma_f32_16x16x32_bf16 v[118:121], v[190:193], v[174:177], v[66:69]
	v_mfma_f32_16x16x32_bf16 v[66:69], v[208:211], v[170:173], v[114:117]
	v_mfma_f32_16x16x32_bf16 v[114:117], v[232:235], v[174:177], v[66:69]
	v_mfma_f32_16x16x32_bf16 v[66:69], v[186:189], v[178:181], v[102:105]
	v_mfma_f32_16x16x32_bf16 v[102:105], v[190:193], v[182:185], v[66:69]
	v_mfma_f32_16x16x32_bf16 v[66:69], v[208:211], v[178:181], v[98:101]
	v_mfma_f32_16x16x32_bf16 v[98:101], v[232:235], v[182:185], v[66:69]
	s_mov_b32 m0, s86
	v_lshl_add_u64 v[178:179], v[238:239], 0, s[22:23]
	s_barrier
	s_nop 2
	ds_read_b128 v[66:69], v230 offset:49152
	ds_read_b128 v[70:73], v230 offset:50176
	ds_read_b128 v[74:77], v230 offset:51200
	ds_read_b128 v[78:81], v230 offset:52224
	ds_read_b128 v[146:149], v230 offset:53248
	ds_read_b128 v[154:157], v230 offset:54272
	ds_read_b128 v[170:173], v230 offset:55296
	ds_read_b128 v[174:177], v230 offset:56320
	global_load_lds_dwordx4 v[178:179], off
	v_lshl_add_u64 v[178:179], v[240:241], 0, s[22:23]
	s_mov_b32 m0, s87
	s_nop 0
	global_load_lds_dwordx4 v[178:179], off
	s_barrier
	s_waitcnt lgkmcnt(0)
	s_waitcnt lgkmcnt(0)
	v_mfma_f32_16x16x32_bf16 v[94:97], v[58:61], v[66:69], v[94:97]
	v_mfma_f32_16x16x32_bf16 v[90:93], v[82:85], v[66:69], v[90:93]
	v_mfma_f32_16x16x32_bf16 v[46:49], v[58:61], v[74:77], v[46:49]
	v_mfma_f32_16x16x32_bf16 v[42:45], v[82:85], v[74:77], v[42:45]
	v_mfma_f32_16x16x32_bf16 v[30:33], v[58:61], v[146:149], v[30:33]
	v_mfma_f32_16x16x32_bf16 v[26:29], v[82:85], v[146:149], v[26:29]
	v_mfma_f32_16x16x32_bf16 v[14:17], v[58:61], v[170:173], v[14:17]
	v_mfma_f32_16x16x32_bf16 v[10:13], v[82:85], v[170:173], v[10:13]
	v_mfma_f32_16x16x32_bf16 v[94:97], v[62:65], v[70:73], v[94:97]
	v_mfma_f32_16x16x32_bf16 v[90:93], v[86:89], v[70:73], v[90:93]
	v_mfma_f32_16x16x32_bf16 v[46:49], v[62:65], v[78:81], v[46:49]
	v_mfma_f32_16x16x32_bf16 v[42:45], v[86:89], v[78:81], v[42:45]
	v_mfma_f32_16x16x32_bf16 v[30:33], v[62:65], v[154:157], v[30:33]
	v_mfma_f32_16x16x32_bf16 v[26:29], v[86:89], v[154:157], v[26:29]
	v_mfma_f32_16x16x32_bf16 v[14:17], v[62:65], v[174:177], v[14:17]
	v_mfma_f32_16x16x32_bf16 v[10:13], v[86:89], v[174:177], v[10:13]
	s_barrier
	s_add_i32 s42, s42, s78
	v_lshl_add_u64 v[58:59], v[242:243], 0, s[22:23]
	s_mov_b32 m0, s42
	s_nop 0
	global_load_lds_dwordx4 v[58:59], off
	v_lshl_add_u64 v[58:59], v[244:245], 0, s[22:23]
	s_add_i32 m0, s42, 0x2000
	s_nop 0
	global_load_lds_dwordx4 v[58:59], off
	s_waitcnt vmcnt(6)
	s_barrier
	v_mfma_f32_16x16x32_bf16 v[50:53], v[186:189], v[66:69], v[50:53]
	v_mfma_f32_16x16x32_bf16 v[86:89], v[190:193], v[70:73], v[50:53]
	v_mfma_f32_16x16x32_bf16 v[50:53], v[208:211], v[66:69], v[54:57]
	v_mfma_f32_16x16x32_bf16 v[38:41], v[186:189], v[74:77], v[38:41]
	v_mfma_f32_16x16x32_bf16 v[34:37], v[208:211], v[74:77], v[34:37]
	v_mfma_f32_16x16x32_bf16 v[22:25], v[186:189], v[146:149], v[22:25]
	v_mfma_f32_16x16x32_bf16 v[18:21], v[208:211], v[146:149], v[18:21]
	v_mfma_f32_16x16x32_bf16 v[6:9], v[186:189], v[170:173], v[6:9]
	v_mfma_f32_16x16x32_bf16 v[2:5], v[208:211], v[170:173], v[2:5]
	v_mfma_f32_16x16x32_bf16 v[82:85], v[232:235], v[70:73], v[50:53]
	v_mfma_f32_16x16x32_bf16 v[38:41], v[190:193], v[78:81], v[38:41]
	v_mfma_f32_16x16x32_bf16 v[34:37], v[232:235], v[78:81], v[34:37]
	v_mfma_f32_16x16x32_bf16 v[22:25], v[190:193], v[154:157], v[22:25]
	v_mfma_f32_16x16x32_bf16 v[18:21], v[232:235], v[154:157], v[18:21]
	v_mfma_f32_16x16x32_bf16 v[6:9], v[190:193], v[174:177], v[6:9]
	v_mfma_f32_16x16x32_bf16 v[2:5], v[232:235], v[174:177], v[2:5]
	s_add_u32 s27, s27, 0x100
	s_addc_u32 s91, s91, 0
	s_add_u32 s36, s36, 0x100
	s_addc_u32 s37, s37, 0
	s_cmp_ge_u32 s92, s32
	s_mov_b32 s42, s92
	s_barrier
	s_cbranch_scc0 .LBB0_1179
	s_cmp_eq_u32 s32, s84
	s_cbranch_scc1 .Ltail_done_1
	s_lshl_b32 s32, s3, 8
	s_add_i32 s32, s32, s85
	v_or_b32_e32 v249, s32, v221
	v_lshlrev_b32_e32 v249, 11, v249
	v_lshl_or_b32 v248, s38, 8, v224
	v_lshl_add_u32 v249, v248, 1, v249
	s_add_i32 s92, s42, 2
	s_add_u32 s72, s36, 0x80
	s_addc_u32 s43, s37, 0
	s_add_i32 s93, 0, 0x10000
	v_add_u32_e32 v1, s93, v223
	ds_read_b128 v[50:53], v1
	ds_read_b128 v[54:57], v1 offset:1024
	ds_read_b128 v[58:61], v1 offset:2048
	ds_read_b128 v[62:65], v1 offset:3072
	s_cmp_eq_u32 s88, s42
	s_cselect_b32 s42, s66, s72
	s_cselect_b32 s43, s67, s43
	s_cselect_b32 s73, s71, s91
	s_cselect_b32 s72, s70, s27
	v_lshl_add_u64 v[178:179], s[36:37], 0, v[206:207]
	s_add_i32 m0, s79, 0xc000
	ds_read_b128 v[66:69], v230
	ds_read_b128 v[70:73], v230 offset:1024
	ds_read_b128 v[74:77], v230 offset:2048
	ds_read_b128 v[78:81], v230 offset:3072
	ds_read_b128 v[146:149], v230 offset:4096
	ds_read_b128 v[154:157], v230 offset:5120
	ds_read_b128 v[170:173], v230 offset:6144
	ds_read_b128 v[174:177], v230 offset:7168
	global_load_lds_dwordx4 v[178:179], off
	v_lshl_add_u64 v[178:179], s[36:37], 0, v[204:205]
	s_add_i32 m0, s79, 0xe000
	s_nop 0
	global_load_lds_dwordx4 v[178:179], off
	s_waitcnt lgkmcnt(8)
	s_barrier
	s_waitcnt lgkmcnt(0)
	s_waitcnt lgkmcnt(0)
	v_mfma_f32_16x16x32_bf16 v[166:169], v[50:53], v[66:69], v[166:169]
	v_mfma_f32_16x16x32_bf16 v[162:165], v[58:61], v[66:69], v[162:165]
	v_mfma_f32_16x16x32_bf16 v[142:145], v[50:53], v[74:77], v[142:145]
	v_mfma_f32_16x16x32_bf16 v[138:141], v[58:61], v[74:77], v[138:141]
	v_mfma_f32_16x16x32_bf16 v[126:129], v[50:53], v[146:149], v[126:129]
	v_mfma_f32_16x16x32_bf16 v[122:125], v[58:61], v[146:149], v[122:125]
	v_mfma_f32_16x16x32_bf16 v[110:113], v[50:53], v[170:173], v[110:113]
	v_mfma_f32_16x16x32_bf16 v[106:109], v[58:61], v[170:173], v[106:109]
	v_mfma_f32_16x16x32_bf16 v[166:169], v[54:57], v[70:73], v[166:169]
	v_mfma_f32_16x16x32_bf16 v[162:165], v[62:65], v[70:73], v[162:165]
	v_mfma_f32_16x16x32_bf16 v[142:145], v[54:57], v[78:81], v[142:145]
	v_mfma_f32_16x16x32_bf16 v[138:141], v[62:65], v[78:81], v[138:141]
	v_mfma_f32_16x16x32_bf16 v[126:129], v[54:57], v[154:157], v[126:129]
	v_mfma_f32_16x16x32_bf16 v[122:125], v[62:65], v[154:157], v[122:125]
	v_mfma_f32_16x16x32_bf16 v[110:113], v[54:57], v[174:177], v[110:113]
	v_mfma_f32_16x16x32_bf16 v[106:109], v[62:65], v[174:177], v[106:109]
	s_barrier
	s_add_i32 s94, 0, 0x14000
	s_add_i32 s93, s93, s78
	v_add_u32_e32 v1, s94, v223
	v_lshl_add_u64 v[214:215], s[72:73], 0, v[202:203]
	s_mov_b32 m0, s93
	ds_read_b128 v[178:181], v1
	ds_read_b128 v[182:185], v1 offset:1024
	ds_read_b128 v[186:189], v1 offset:2048
	ds_read_b128 v[190:193], v1 offset:3072
	v_lshl_add_u64 v[236:237], s[72:73], 0, v[200:201]
	s_add_i32 m0, s93, 0x2000
	s_nop 0
	v_mov_b32_e32 v250, v249
	global_load_dword v251, v250, s[48:49]
	global_load_dword v251, v250, s[48:49] offset:256
	s_barrier
	s_waitcnt lgkmcnt(0)
	s_waitcnt lgkmcnt(0)
	v_mfma_f32_16x16x32_bf16 v[158:161], v[178:181], v[66:69], v[158:161]
	v_mfma_f32_16x16x32_bf16 v[66:69], v[186:189], v[66:69], v[150:153]
	v_mfma_f32_16x16x32_bf16 v[158:161], v[182:185], v[70:73], v[158:161]
	v_mfma_f32_16x16x32_bf16 v[66:69], v[190:193], v[70:73], v[66:69]
	v_mfma_f32_16x16x32_bf16 v[70:73], v[178:181], v[74:77], v[134:137]
	v_mfma_f32_16x16x32_bf16 v[74:77], v[186:189], v[74:77], v[130:133]
	v_mfma_f32_16x16x32_bf16 v[114:117], v[186:189], v[146:149], v[114:117]
	v_mfma_f32_16x16x32_bf16 v[102:105], v[178:181], v[170:173], v[102:105]
	v_mfma_f32_16x16x32_bf16 v[98:101], v[186:189], v[170:173], v[98:101]
	v_mfma_f32_16x16x32_bf16 v[70:73], v[182:185], v[78:81], v[70:73]
	v_mfma_f32_16x16x32_bf16 v[74:77], v[190:193], v[78:81], v[74:77]
	v_mfma_f32_16x16x32_bf16 v[78:81], v[178:181], v[146:149], v[118:121]
	v_mfma_f32_16x16x32_bf16 v[114:117], v[190:193], v[154:157], v[114:117]
	v_mfma_f32_16x16x32_bf16 v[102:105], v[182:185], v[174:177], v[102:105]
	v_mfma_f32_16x16x32_bf16 v[98:101], v[190:193], v[174:177], v[98:101]
	v_mfma_f32_16x16x32_bf16 v[78:81], v[182:185], v[154:157], v[78:81]
	s_mov_b32 m0, s79
	v_lshl_add_u64 v[238:239], s[42:43], 0, v[202:203]
	s_barrier
	ds_read_b128 v[118:121], v230 offset:16384
	ds_read_b128 v[130:133], v230 offset:17408
	ds_read_b128 v[134:137], v230 offset:18432
	ds_read_b128 v[146:149], v230 offset:19456
	ds_read_b128 v[150:153], v230 offset:20480
	ds_read_b128 v[154:157], v230 offset:21504
	ds_read_b128 v[170:173], v230 offset:22528
	ds_read_b128 v[174:177], v230 offset:23552
	v_lshl_add_u64 v[240:241], s[42:43], 0, v[200:201]
	s_mov_b32 m0, s80
	s_nop 0
	v_add_u32_e32 v250, 0x8000, v249
	global_load_dword v251, v250, s[48:49]
	global_load_dword v251, v250, s[48:49] offset:256
	s_barrier
	s_waitcnt lgkmcnt(0)
	s_waitcnt lgkmcnt(0)
	v_mfma_f32_16x16x32_bf16 v[94:97], v[50:53], v[118:121], v[94:97]
	v_mfma_f32_16x16x32_bf16 v[90:93], v[58:61], v[118:121], v[90:93]
	v_mfma_f32_16x16x32_bf16 v[46:49], v[50:53], v[134:137], v[46:49]
	v_mfma_f32_16x16x32_bf16 v[42:45], v[58:61], v[134:137], v[42:45]
	v_mfma_f32_16x16x32_bf16 v[30:33], v[50:53], v[150:153], v[30:33]
	v_mfma_f32_16x16x32_bf16 v[26:29], v[58:61], v[150:153], v[26:29]
	v_mfma_f32_16x16x32_bf16 v[14:17], v[50:53], v[170:173], v[14:17]
	v_mfma_f32_16x16x32_bf16 v[10:13], v[58:61], v[170:173], v[10:13]
	v_mfma_f32_16x16x32_bf16 v[94:97], v[54:57], v[130:133], v[94:97]
	v_mfma_f32_16x16x32_bf16 v[90:93], v[62:65], v[130:133], v[90:93]
	v_mfma_f32_16x16x32_bf16 v[46:49], v[54:57], v[146:149], v[46:49]
	v_mfma_f32_16x16x32_bf16 v[42:45], v[62:65], v[146:149], v[42:45]
	v_mfma_f32_16x16x32_bf16 v[30:33], v[54:57], v[154:157], v[30:33]
	v_mfma_f32_16x16x32_bf16 v[26:29], v[62:65], v[154:157], v[26:29]
	v_mfma_f32_16x16x32_bf16 v[14:17], v[54:57], v[174:177], v[14:17]
	v_mfma_f32_16x16x32_bf16 v[10:13], v[62:65], v[174:177], v[10:13]
	s_barrier
	s_add_u32 s72, s72, s4
	s_addc_u32 s73, s73, 0
	s_add_i32 s93, s94, s78
	v_lshl_add_u64 v[242:243], s[72:73], 0, v[202:203]
	s_mov_b32 m0, s93
	v_lshl_add_u64 v[244:245], s[72:73], 0, v[200:201]
	s_add_i32 m0, s93, 0x2000
	s_nop 0
	v_add_u32_e32 v250, 0x10000, v249
	global_load_dword v251, v250, s[48:49]
	global_load_dword v251, v250, s[48:49] offset:256
	s_waitcnt vmcnt(6)
	s_barrier
	v_mfma_f32_16x16x32_bf16 v[38:41], v[178:181], v[134:137], v[38:41]
	v_mfma_f32_16x16x32_bf16 v[34:37], v[186:189], v[134:137], v[34:37]
	v_mfma_f32_16x16x32_bf16 v[22:25], v[178:181], v[150:153], v[22:25]
	v_mfma_f32_16x16x32_bf16 v[18:21], v[186:189], v[150:153], v[18:21]
	v_mfma_f32_16x16x32_bf16 v[6:9], v[178:181], v[170:173], v[6:9]
	v_mfma_f32_16x16x32_bf16 v[2:5], v[186:189], v[170:173], v[2:5]
	v_mfma_f32_16x16x32_bf16 v[50:53], v[178:181], v[118:121], v[86:89]
	v_mfma_f32_16x16x32_bf16 v[54:57], v[186:189], v[118:121], v[82:85]
	v_mfma_f32_16x16x32_bf16 v[38:41], v[182:185], v[146:149], v[38:41]
	v_mfma_f32_16x16x32_bf16 v[34:37], v[190:193], v[146:149], v[34:37]
	v_mfma_f32_16x16x32_bf16 v[22:25], v[182:185], v[154:157], v[22:25]
	v_mfma_f32_16x16x32_bf16 v[18:21], v[190:193], v[154:157], v[18:21]
	v_mfma_f32_16x16x32_bf16 v[6:9], v[182:185], v[174:177], v[6:9]
	v_mfma_f32_16x16x32_bf16 v[2:5], v[190:193], v[174:177], v[2:5]
	v_mfma_f32_16x16x32_bf16 v[50:53], v[182:185], v[130:133], v[50:53]
	v_mfma_f32_16x16x32_bf16 v[54:57], v[190:193], v[130:133], v[54:57]
	s_add_i32 s72, 0, 0x18000
	v_add_u32_e32 v1, s72, v223
	s_barrier
	ds_read_b128 v[58:61], v1
	ds_read_b128 v[62:65], v1 offset:1024
	ds_read_b128 v[82:85], v1 offset:2048
	ds_read_b128 v[86:89], v1 offset:3072
	s_add_u32 s42, s42, s4
	s_addc_u32 s43, s43, 0
	s_mov_b32 m0, s81
	v_lshl_add_u64 v[134:135], s[42:43], 0, v[202:203]
	ds_read_b128 v[118:121], v230 offset:32768
	ds_read_b128 v[130:133], v230 offset:33792
	ds_read_b128 v[146:149], v230 offset:34816
	ds_read_b128 v[154:157], v230 offset:35840
	ds_read_b128 v[170:173], v230 offset:36864
	ds_read_b128 v[174:177], v230 offset:37888
	ds_read_b128 v[178:181], v230 offset:38912
	ds_read_b128 v[182:185], v230 offset:39936
	v_lshl_add_u64 v[134:135], s[42:43], 0, v[200:201]
	s_mov_b32 m0, s82
	s_nop 0
	s_waitcnt lgkmcnt(8)
	v_add_u32_e32 v250, 0x18000, v249
	global_load_dword v251, v250, s[48:49]
	global_load_dword v251, v250, s[48:49] offset:256
	s_barrier
	s_waitcnt lgkmcnt(0)
	s_waitcnt lgkmcnt(0)
	v_mfma_f32_16x16x32_bf16 v[134:137], v[58:61], v[118:121], v[166:169]
	v_mfma_f32_16x16x32_bf16 v[166:169], v[62:65], v[130:133], v[134:137]
	v_mfma_f32_16x16x32_bf16 v[134:137], v[82:85], v[118:121], v[162:165]
	v_mfma_f32_16x16x32_bf16 v[162:165], v[86:89], v[130:133], v[134:137]
	v_mfma_f32_16x16x32_bf16 v[134:137], v[58:61], v[146:149], v[142:145]
	v_mfma_f32_16x16x32_bf16 v[142:145], v[62:65], v[154:157], v[134:137]
	v_mfma_f32_16x16x32_bf16 v[134:137], v[82:85], v[146:149], v[138:141]
	v_mfma_f32_16x16x32_bf16 v[126:129], v[58:61], v[170:173], v[126:129]
	v_mfma_f32_16x16x32_bf16 v[122:125], v[82:85], v[170:173], v[122:125]
	v_mfma_f32_16x16x32_bf16 v[110:113], v[58:61], v[178:181], v[110:113]
	v_mfma_f32_16x16x32_bf16 v[106:109], v[82:85], v[178:181], v[106:109]
	v_mfma_f32_16x16x32_bf16 v[138:141], v[86:89], v[154:157], v[134:137]
	v_mfma_f32_16x16x32_bf16 v[126:129], v[62:65], v[174:177], v[126:129]
	v_mfma_f32_16x16x32_bf16 v[122:125], v[86:89], v[174:177], v[122:125]
	v_mfma_f32_16x16x32_bf16 v[110:113], v[62:65], v[182:185], v[110:113]
	v_mfma_f32_16x16x32_bf16 v[106:109], v[86:89], v[182:185], v[106:109]
	s_barrier
	s_add_i32 s42, 0, 0x1c000
	s_add_i32 s43, s72, s78
	v_add_u32_e32 v1, s42, v223
	v_lshl_add_u64 v[134:135], v[214:215], 0, s[22:23]
	s_mov_b32 m0, s43
	ds_read_b128 v[186:189], v1
	ds_read_b128 v[190:193], v1 offset:1024
	ds_read_b128 v[208:211], v1 offset:2048
	ds_read_b128 v[232:235], v1 offset:3072
	v_lshl_add_u64 v[134:135], v[236:237], 0, s[22:23]
	s_add_i32 m0, s43, 0x2000
	s_nop 0
	v_add_u32_e32 v250, 0x40000, v249
	global_load_dword v251, v250, s[48:49]
	global_load_dword v251, v250, s[48:49] offset:256
	s_barrier
	s_waitcnt lgkmcnt(0)
	s_waitcnt lgkmcnt(0)
	v_mfma_f32_16x16x32_bf16 v[66:69], v[208:211], v[118:121], v[66:69]
	v_mfma_f32_16x16x32_bf16 v[134:137], v[186:189], v[118:121], v[158:161]
	v_mfma_f32_16x16x32_bf16 v[150:153], v[232:235], v[130:133], v[66:69]
	v_mfma_f32_16x16x32_bf16 v[66:69], v[186:189], v[146:149], v[70:73]
	v_mfma_f32_16x16x32_bf16 v[158:161], v[190:193], v[130:133], v[134:137]
	v_mfma_f32_16x16x32_bf16 v[134:137], v[190:193], v[154:157], v[66:69]
	v_mfma_f32_16x16x32_bf16 v[66:69], v[208:211], v[146:149], v[74:77]
	v_mfma_f32_16x16x32_bf16 v[130:133], v[232:235], v[154:157], v[66:69]
	v_mfma_f32_16x16x32_bf16 v[66:69], v[186:189], v[170:173], v[78:81]
	v_mfma_f32_16x16x32_bf16 v[118:121], v[190:193], v[174:177], v[66:69]
	v_mfma_f32_16x16x32_bf16 v[66:69], v[208:211], v[170:173], v[114:117]
	v_mfma_f32_16x16x32_bf16 v[114:117], v[232:235], v[174:177], v[66:69]
	v_mfma_f32_16x16x32_bf16 v[66:69], v[186:189], v[178:181], v[102:105]
	v_mfma_f32_16x16x32_bf16 v[102:105], v[190:193], v[182:185], v[66:69]
	v_mfma_f32_16x16x32_bf16 v[66:69], v[208:211], v[178:181], v[98:101]
	v_mfma_f32_16x16x32_bf16 v[98:101], v[232:235], v[182:185], v[66:69]
	s_mov_b32 m0, s86
	v_lshl_add_u64 v[178:179], v[238:239], 0, s[22:23]
	s_barrier
	s_nop 2
	ds_read_b128 v[66:69], v230 offset:49152
	ds_read_b128 v[70:73], v230 offset:50176
	ds_read_b128 v[74:77], v230 offset:51200
	ds_read_b128 v[78:81], v230 offset:52224
	ds_read_b128 v[146:149], v230 offset:53248
	ds_read_b128 v[154:157], v230 offset:54272
	ds_read_b128 v[170:173], v230 offset:55296
	ds_read_b128 v[174:177], v230 offset:56320
	v_lshl_add_u64 v[178:179], v[240:241], 0, s[22:23]
	s_mov_b32 m0, s87
	s_nop 0
	v_add_u32_e32 v250, 0x48000, v249
	global_load_dword v251, v250, s[48:49]
	global_load_dword v251, v250, s[48:49] offset:256
	s_barrier
	s_waitcnt lgkmcnt(0)
	s_waitcnt lgkmcnt(0)
	v_mfma_f32_16x16x32_bf16 v[94:97], v[58:61], v[66:69], v[94:97]
	v_mfma_f32_16x16x32_bf16 v[90:93], v[82:85], v[66:69], v[90:93]
	v_mfma_f32_16x16x32_bf16 v[46:49], v[58:61], v[74:77], v[46:49]
	v_mfma_f32_16x16x32_bf16 v[42:45], v[82:85], v[74:77], v[42:45]
	v_mfma_f32_16x16x32_bf16 v[30:33], v[58:61], v[146:149], v[30:33]
	v_mfma_f32_16x16x32_bf16 v[26:29], v[82:85], v[146:149], v[26:29]
	v_mfma_f32_16x16x32_bf16 v[14:17], v[58:61], v[170:173], v[14:17]
	v_mfma_f32_16x16x32_bf16 v[10:13], v[82:85], v[170:173], v[10:13]
	v_mfma_f32_16x16x32_bf16 v[94:97], v[62:65], v[70:73], v[94:97]
	v_mfma_f32_16x16x32_bf16 v[90:93], v[86:89], v[70:73], v[90:93]
	v_mfma_f32_16x16x32_bf16 v[46:49], v[62:65], v[78:81], v[46:49]
	v_mfma_f32_16x16x32_bf16 v[42:45], v[86:89], v[78:81], v[42:45]
	v_mfma_f32_16x16x32_bf16 v[30:33], v[62:65], v[154:157], v[30:33]
	v_mfma_f32_16x16x32_bf16 v[26:29], v[86:89], v[154:157], v[26:29]
	v_mfma_f32_16x16x32_bf16 v[14:17], v[62:65], v[174:177], v[14:17]
	v_mfma_f32_16x16x32_bf16 v[10:13], v[86:89], v[174:177], v[10:13]
	s_barrier
	s_add_i32 s42, s42, s78
	v_lshl_add_u64 v[58:59], v[242:243], 0, s[22:23]
	s_mov_b32 m0, s42
	s_nop 0
	v_lshl_add_u64 v[58:59], v[244:245], 0, s[22:23]
	s_add_i32 m0, s42, 0x2000
	s_nop 0
	v_add_u32_e32 v250, 0x50000, v249
	global_load_dword v251, v250, s[48:49]
	global_load_dword v251, v250, s[48:49] offset:256
	s_barrier
	v_mfma_f32_16x16x32_bf16 v[50:53], v[186:189], v[66:69], v[50:53]
	v_mfma_f32_16x16x32_bf16 v[86:89], v[190:193], v[70:73], v[50:53]
	v_mfma_f32_16x16x32_bf16 v[50:53], v[208:211], v[66:69], v[54:57]
	v_mfma_f32_16x16x32_bf16 v[38:41], v[186:189], v[74:77], v[38:41]
	v_mfma_f32_16x16x32_bf16 v[34:37], v[208:211], v[74:77], v[34:37]
	v_mfma_f32_16x16x32_bf16 v[22:25], v[186:189], v[146:149], v[22:25]
	v_mfma_f32_16x16x32_bf16 v[18:21], v[208:211], v[146:149], v[18:21]
	v_mfma_f32_16x16x32_bf16 v[6:9], v[186:189], v[170:173], v[6:9]
	v_mfma_f32_16x16x32_bf16 v[2:5], v[208:211], v[170:173], v[2:5]
	v_mfma_f32_16x16x32_bf16 v[82:85], v[232:235], v[70:73], v[50:53]
	v_mfma_f32_16x16x32_bf16 v[38:41], v[190:193], v[78:81], v[38:41]
	v_mfma_f32_16x16x32_bf16 v[34:37], v[232:235], v[78:81], v[34:37]
	v_mfma_f32_16x16x32_bf16 v[22:25], v[190:193], v[154:157], v[22:25]
	v_mfma_f32_16x16x32_bf16 v[18:21], v[232:235], v[154:157], v[18:21]
	v_mfma_f32_16x16x32_bf16 v[6:9], v[190:193], v[174:177], v[6:9]
	v_mfma_f32_16x16x32_bf16 v[2:5], v[232:235], v[174:177], v[2:5]
	s_add_u32 s27, s27, 0x100
	s_addc_u32 s91, s91, 0
	s_add_u32 s36, s36, 0x100
	s_addc_u32 s37, s37, 0
	s_cmp_ge_u32 s92, s84
	s_mov_b32 s42, s92
	s_barrier
